# GEMM epilogues (SwiGLU, hybrid in-proj, r/k/v, residual) run at raised wave priority
# baseline (speedup 1.0000x reference)
;     ...
;       for (int kt = 0; kt < KT; kt++) {
;         {
;           const bf16_t* apx = ap;
;           int kc = kt * 64;
;           if (SHIFT && kc >= 1024) { apx = ap - lda; kc -= 1024; }
; #pragma unroll
;           for (int i = 0; i < 8; i++)
;             __builtin_amdgcn_global_load_lds((const unsigned*)(apx + i * a32 + kc), sbase + i * 1024, 16, 0, 0);
; #pragma unroll
;           for (int i = 0; i < 4; i++)
;             __builtin_amdgcn_global_load_lds((const unsigned*)(bp + i * b32 + kt * 64), sbase + 8192 + i * 1024, 16, 0, 0);
;         }
;         asm volatile("s_waitcnt vmcnt(0)" ::: "memory");
;         __syncthreads();
; #pragma unroll
;         for (int kk = 0; kk < 2; kk++) {
;           bf16x8 af[MI], bfr[4];
;           const int csw = (((kk * 4 + fq) ^ fsw) << 3);
; #pragma unroll
;           for (int mi = 0; mi < MI; mi++) af[mi] = *(const bf16x8*)(smem + (wm * 128 + mi * 16 + fr) * 64 + csw);
; #pragma unroll
;           for (int ni = 0; ni < 4; ni++) bfr[ni] = *(const bf16x8*)(smem + 16384 + (wn * 64 + ni * 16 + fr) * 64 + csw);
; #pragma unroll
;           for (int mi = 0; mi < MI; mi++)
; #pragma unroll
;             for (int ni = 0; ni < 4; ni++)
;               acc[mi][ni] = __builtin_amdgcn_mfma_f32_16x16x32_bf16(bfr[ni], af[mi], acc[mi][ni], 0, 0, 0);
;         }
;         __syncthreads();
;       }
.LBB0_618:
	s_cmp_gt_u32 s6, 15
	s_cselect_b64 s[10:11], -1, 0
	s_add_i32 s7, s5, 0xfffffc00
	s_and_b64 s[10:11], s[10:11], exec
	s_cselect_b32 s11, -1, 0
	s_cselect_b32 s10, 0xfffff800, 0
	v_lshl_add_u64 v[138:139], v[170:171], 0, s[10:11]
	s_cselect_b32 s10, s7, s5
	s_ashr_i32 s11, s10, 31
	v_lshl_add_u64 v[138:139], s[10:11], 1, v[138:139]
	v_readfirstlane_b32 s7, v174
	v_add_u32_e32 v8, 0x1000, v174
	v_lshl_add_u64 v[140:141], v[138:139], 0, s[16:17]
	s_mov_b32 m0, s7
	v_readfirstlane_b32 s7, v8
	v_add_u32_e32 v8, 0x2000, v174
	global_load_lds_dwordx4 v[140:141], off
	v_lshl_add_u64 v[140:141], v[138:139], 0, s[18:19]
	s_mov_b32 m0, s7
	v_readfirstlane_b32 s7, v8
	v_add_u32_e32 v8, 0x3000, v174
	global_load_lds_dwordx4 v[140:141], off
	v_lshl_add_u64 v[140:141], v[138:139], 0, s[20:21]
	s_mov_b32 m0, s7
	v_readfirstlane_b32 s7, v8
	v_add_u32_e32 v8, 0x4000, v174
	global_load_lds_dwordx4 v[140:141], off
	v_lshl_add_u64 v[140:141], v[138:139], 0, s[22:23]
	s_mov_b32 m0, s7
	v_readfirstlane_b32 s7, v8
	v_add_u32_e32 v8, 0x5000, v174
	global_load_lds_dwordx4 v[140:141], off
	v_lshl_add_u64 v[140:141], v[138:139], 0, s[24:25]
	s_mov_b32 m0, s7
	v_readfirstlane_b32 s7, v8
	v_add_u32_e32 v8, 0x6000, v174
	global_load_lds_dwordx4 v[140:141], off
	v_lshl_add_u64 v[140:141], v[138:139], 0, s[26:27]
	s_mov_b32 m0, s7
	v_readfirstlane_b32 s7, v8
	v_add_u32_e32 v8, 0x7000, v174
	global_load_lds_dwordx4 v[140:141], off
	v_lshl_add_u64 v[140:141], v[138:139], 0, s[14:15]
	s_mov_b32 m0, s7
	v_readfirstlane_b32 s7, v8
	global_load_lds_dwordx4 v[140:141], off
	v_lshl_add_u64 v[138:139], v[138:139], 0, s[28:29]
	s_mov_b32 m0, s7
	v_add_u32_e32 v8, 0x8000, v174
	global_load_lds_dwordx4 v[138:139], off
	v_lshl_add_u64 v[138:139], v[172:173], 0, s[0:1]
	s_mov_b64 s[10:11], 0x6180000
	v_readfirstlane_b32 s7, v8
	v_add_u32_e32 v8, 0x9000, v174
	v_lshl_add_u64 v[140:141], v[138:139], 0, s[10:11]
	s_mov_b32 m0, s7
	s_mov_b64 s[10:11], 0x61a0000
	v_readfirstlane_b32 s7, v8
	v_add_u32_e32 v8, 0xa000, v174
	global_load_lds_dwordx4 v[140:141], off
	v_lshl_add_u64 v[140:141], v[138:139], 0, s[10:11]
	s_mov_b32 m0, s7
	s_mov_b64 s[10:11], 0x61c0000
	v_readfirstlane_b32 s7, v8
	v_add_u32_e32 v8, 0xb000, v174
	global_load_lds_dwordx4 v[140:141], off
	v_lshl_add_u64 v[140:141], v[138:139], 0, s[10:11]
	s_mov_b32 m0, s7
	s_mov_b64 s[10:11], 0x61e0000
	v_readfirstlane_b32 s7, v8
	global_load_lds_dwordx4 v[140:141], off
	v_lshl_add_u64 v[138:139], v[138:139], 0, s[10:11]
	s_mov_b32 m0, s7
	v_add_u32_e32 v8, v177, v178
	global_load_lds_dwordx4 v[138:139], off
	s_waitcnt vmcnt(0)
	s_waitcnt vmcnt(0) lgkmcnt(0)
	s_barrier
	ds_read_b128 v[182:185], v8
	ds_read_b128 v[186:189], v8 offset:2048
	ds_read_b128 v[158:161], v8 offset:4096
	ds_read_b128 v[154:157], v8 offset:6144
	ds_read_b128 v[150:153], v8 offset:8192
	ds_read_b128 v[146:149], v8 offset:10240
	ds_read_b128 v[142:145], v8 offset:12288
	ds_read_b128 v[138:141], v8 offset:14336
	ds_read_b128 v[190:193], v180 offset:32768
	ds_read_b128 v[194:197], v180 offset:34816
	ds_read_b128 v[198:201], v180 offset:36864
	ds_read_b128 v[202:205], v180 offset:38912
	v_add_u32_e32 v8, v179, v178
	s_waitcnt lgkmcnt(3)
	v_mfma_f32_16x16x32_bf16 v[134:137], v[190:193], v[182:185], v[134:137]
	s_add_i32 s6, s6, 1
	s_add_u32 s0, s0, 0x80
	s_addc_u32 s1, s1, 0
	s_waitcnt lgkmcnt(2)
	v_mfma_f32_16x16x32_bf16 v[130:133], v[194:197], v[182:185], v[130:133]
	s_add_i32 s5, s5, 64
	s_cmpk_eq_i32 s0, 0x1000
	s_waitcnt lgkmcnt(1)
	v_mfma_f32_16x16x32_bf16 v[126:129], v[198:201], v[182:185], v[126:129]
	s_waitcnt lgkmcnt(0)
	v_mfma_f32_16x16x32_bf16 v[122:125], v[202:205], v[182:185], v[122:125]
	v_mfma_f32_16x16x32_bf16 v[118:121], v[190:193], v[186:189], v[118:121]
	v_mfma_f32_16x16x32_bf16 v[114:117], v[194:197], v[186:189], v[114:117]
	v_mfma_f32_16x16x32_bf16 v[110:113], v[198:201], v[186:189], v[110:113]
	v_mfma_f32_16x16x32_bf16 v[106:109], v[202:205], v[186:189], v[106:109]
	v_mfma_f32_16x16x32_bf16 v[102:105], v[190:193], v[158:161], v[102:105]
	v_mfma_f32_16x16x32_bf16 v[98:101], v[194:197], v[158:161], v[98:101]
	v_mfma_f32_16x16x32_bf16 v[94:97], v[198:201], v[158:161], v[94:97]
	v_mfma_f32_16x16x32_bf16 v[90:93], v[202:205], v[158:161], v[90:93]
	v_mfma_f32_16x16x32_bf16 v[86:89], v[190:193], v[154:157], v[86:89]
	v_mfma_f32_16x16x32_bf16 v[82:85], v[194:197], v[154:157], v[82:85]
	v_mfma_f32_16x16x32_bf16 v[78:81], v[198:201], v[154:157], v[78:81]
	v_mfma_f32_16x16x32_bf16 v[74:77], v[202:205], v[154:157], v[74:77]
	v_mfma_f32_16x16x32_bf16 v[70:73], v[190:193], v[150:153], v[70:73]
	v_mfma_f32_16x16x32_bf16 v[66:69], v[194:197], v[150:153], v[66:69]
	v_mfma_f32_16x16x32_bf16 v[62:65], v[198:201], v[150:153], v[62:65]
	v_mfma_f32_16x16x32_bf16 v[58:61], v[202:205], v[150:153], v[58:61]
	v_mfma_f32_16x16x32_bf16 v[54:57], v[190:193], v[146:149], v[54:57]
	v_mfma_f32_16x16x32_bf16 v[50:53], v[194:197], v[146:149], v[50:53]
	v_mfma_f32_16x16x32_bf16 v[46:49], v[198:201], v[146:149], v[46:49]
	v_mfma_f32_16x16x32_bf16 v[42:45], v[202:205], v[146:149], v[42:45]
	v_mfma_f32_16x16x32_bf16 v[38:41], v[190:193], v[142:145], v[38:41]
	v_mfma_f32_16x16x32_bf16 v[34:37], v[194:197], v[142:145], v[34:37]
	v_mfma_f32_16x16x32_bf16 v[30:33], v[198:201], v[142:145], v[30:33]
	v_mfma_f32_16x16x32_bf16 v[26:29], v[202:205], v[142:145], v[26:29]
	v_mfma_f32_16x16x32_bf16 v[22:25], v[190:193], v[138:141], v[22:25]
	v_mfma_f32_16x16x32_bf16 v[18:21], v[194:197], v[138:141], v[18:21]
	v_mfma_f32_16x16x32_bf16 v[14:17], v[198:201], v[138:141], v[14:17]
	v_mfma_f32_16x16x32_bf16 v[10:13], v[202:205], v[138:141], v[10:13]
	ds_read_b128 v[138:141], v8
	ds_read_b128 v[142:145], v8 offset:2048
	ds_read_b128 v[146:149], v8 offset:4096
	ds_read_b128 v[150:153], v8 offset:6144
	ds_read_b128 v[154:157], v8 offset:8192
	ds_read_b128 v[158:161], v8 offset:10240
	ds_read_b128 v[182:185], v8 offset:12288
	ds_read_b128 v[186:189], v8 offset:14336
	ds_read_b128 v[190:193], v181 offset:32768
	ds_read_b128 v[194:197], v181 offset:34816
	ds_read_b128 v[198:201], v181 offset:36864
	ds_read_b128 v[202:205], v181 offset:38912
	s_waitcnt lgkmcnt(0)
	s_barrier
; __device__ __forceinline__ float sigmoidf_(float x) { return __builtin_amdgcn_rcpf(1.f + __expf(-x)); }
;     ...
;           for (int mi = 0; mi < MI; mi++)
; #pragma unroll
;             for (int ni = 0; ni < 4; ni++)
;               acc[mi][ni] = __builtin_amdgcn_mfma_f32_16x16x32_bf16(bfr[ni], af[mi], acc[mi][ni], 0, 0, 0);
;     ...
;             } else if constexpr (EPI == EPI_RK1) {
;               uint2 o;
;               if (col < 3072) {
;                 o.x = pack2(a[0], a[1]); o.y = pack2(a[2], a[3]);
;                 *(uint2*)(e.b0 + (row * (unsigned)RKLD + col)) = o;
;               } else if (col < 3392) {
;                 if (col < 3136) { o.x = pack2(tanhf(a[0]), tanhf(a[1])); o.y = pack2(tanhf(a[2]), tanhf(a[3])); }
;                 else if (col < 3200) { o.x = pack2(a[0], a[1]); o.y = pack2(a[2], a[3]); }
;                 else if (col < 3360) { o.x = pack2(sigmoidf_(a[0]), sigmoidf_(a[1])); o.y = pack2(sigmoidf_(a[2]), sigmoidf_(a[3])); }
;                 else { o.x = 0u; o.y = 0u; }
;                 *(uint2*)(e.b1 + (row * (unsigned)MIDLD + (col - 3072))) = o;
;               }
	v_mfma_f32_16x16x32_bf16 v[134:137], v[190:193], v[138:141], v[134:137]
	v_mfma_f32_16x16x32_bf16 v[130:133], v[194:197], v[138:141], v[130:133]
	v_mfma_f32_16x16x32_bf16 v[126:129], v[198:201], v[138:141], v[126:129]
	v_mfma_f32_16x16x32_bf16 v[122:125], v[202:205], v[138:141], v[122:125]
	v_mfma_f32_16x16x32_bf16 v[118:121], v[190:193], v[142:145], v[118:121]
	v_mfma_f32_16x16x32_bf16 v[114:117], v[194:197], v[142:145], v[114:117]
	v_mfma_f32_16x16x32_bf16 v[110:113], v[198:201], v[142:145], v[110:113]
	v_mfma_f32_16x16x32_bf16 v[106:109], v[202:205], v[142:145], v[106:109]
	v_mfma_f32_16x16x32_bf16 v[102:105], v[190:193], v[146:149], v[102:105]
	v_mfma_f32_16x16x32_bf16 v[98:101], v[194:197], v[146:149], v[98:101]
	v_mfma_f32_16x16x32_bf16 v[94:97], v[198:201], v[146:149], v[94:97]
	v_mfma_f32_16x16x32_bf16 v[90:93], v[202:205], v[146:149], v[90:93]
	v_mfma_f32_16x16x32_bf16 v[86:89], v[190:193], v[150:153], v[86:89]
	v_mfma_f32_16x16x32_bf16 v[82:85], v[194:197], v[150:153], v[82:85]
	v_mfma_f32_16x16x32_bf16 v[78:81], v[198:201], v[150:153], v[78:81]
	v_mfma_f32_16x16x32_bf16 v[74:77], v[202:205], v[150:153], v[74:77]
	v_mfma_f32_16x16x32_bf16 v[70:73], v[190:193], v[154:157], v[70:73]
	v_mfma_f32_16x16x32_bf16 v[66:69], v[194:197], v[154:157], v[66:69]
	v_mfma_f32_16x16x32_bf16 v[62:65], v[198:201], v[154:157], v[62:65]
	v_mfma_f32_16x16x32_bf16 v[58:61], v[202:205], v[154:157], v[58:61]
	v_mfma_f32_16x16x32_bf16 v[54:57], v[190:193], v[158:161], v[54:57]
	v_mfma_f32_16x16x32_bf16 v[50:53], v[194:197], v[158:161], v[50:53]
	v_mfma_f32_16x16x32_bf16 v[46:49], v[198:201], v[158:161], v[46:49]
	v_mfma_f32_16x16x32_bf16 v[42:45], v[202:205], v[158:161], v[42:45]
	v_mfma_f32_16x16x32_bf16 v[38:41], v[190:193], v[182:185], v[38:41]
	v_mfma_f32_16x16x32_bf16 v[34:37], v[194:197], v[182:185], v[34:37]
	v_mfma_f32_16x16x32_bf16 v[30:33], v[198:201], v[182:185], v[30:33]
	v_mfma_f32_16x16x32_bf16 v[26:29], v[202:205], v[182:185], v[26:29]
	v_mfma_f32_16x16x32_bf16 v[22:25], v[190:193], v[186:189], v[22:25]
	v_mfma_f32_16x16x32_bf16 v[18:21], v[194:197], v[186:189], v[18:21]
	v_mfma_f32_16x16x32_bf16 v[14:17], v[198:201], v[186:189], v[14:17]
	v_mfma_f32_16x16x32_bf16 v[10:13], v[202:205], v[186:189], v[10:13]
	s_cbranch_scc0 .LBB0_618
	v_add_u32_e32 v142, s4, v176
	s_movk_i32 s0, 0x140
	s_cmpk_gt_u32 s13, 0xbff
	v_or_b32_e32 v140, s13, v175
	v_mul_lo_u32 v8, v142, s0
	s_cselect_b64 s[4:5], -1, 0
	s_movk_i32 s0, 0xd40
	v_add_u32_e32 v141, 0xfffff400, v8
	s_mov_b64 s[6:7], -1
	s_and_b64 vcc, exec, s[4:5]
	v_cmp_gt_u32_e64 s[0:1], s0, v140
	s_mov_b32 s28, s30
	s_mov_b64 s[26:27], s[48:49]
	s_cbranch_vccnz .Lrk_slow
;     ...
;       const unsigned rb2 = (unsigned)(m0 + wm * (BM / 2) + fr);
;       const unsigned cb2 = (unsigned)(n0 + wn * 64 + fq * 4);
; #pragma unroll
;       for (int mi = 0; mi < MI; mi++) {
;         const unsigned row = rb2 + mi * 16;
;     ...
;             } else if constexpr (EPI == EPI_RK1) {
;               uint2 o;
;               if (col < 3072) {
;                 o.x = pack2(a[0], a[1]); o.y = pack2(a[2], a[3]);
;                 *(uint2*)(e.b0 + (row * (unsigned)RKLD + col)) = o;
	s_setprio 2
	s_movk_i32 s0, 0xc00
	v_mul_lo_u32 v138, v142, s0
	v_bfe_u32 v139, v2, 4, 1
	v_add_u32_e32 v138, v138, v140
	v_mul_u32_u24_e32 v139, 12, v139
	s_nop 0
	v_add_u32_e32 v138, v138, v139
	v_cvt_pk_bf16_f32 v190, v134, v135
	v_cvt_pk_bf16_f32 v191, v136, v137
	v_cvt_pk_bf16_f32 v192, v130, v131
	v_cvt_pk_bf16_f32 v193, v132, v133
	v_mov_b32_e32 v8, v138
	v_lshl_add_u64 v[202:203], v[8:9], 1, s[52:53]
	v_permlane16_swap_b32 v190, v192
	v_permlane16_swap_b32 v191, v193
	s_nop 1
	global_store_dwordx4 v[202:203], v[190:193], off
	v_cvt_pk_bf16_f32 v194, v126, v127
	v_cvt_pk_bf16_f32 v195, v128, v129
	v_cvt_pk_bf16_f32 v196, v122, v123
	v_cvt_pk_bf16_f32 v197, v124, v125
	v_add_u32_e32 v8, 0x20, v138
	v_lshl_add_u64 v[204:205], v[8:9], 1, s[52:53]
	v_permlane16_swap_b32 v194, v196
	v_permlane16_swap_b32 v195, v197
	s_nop 1
	global_store_dwordx4 v[204:205], v[194:197], off
	v_cvt_pk_bf16_f32 v198, v118, v119
	v_cvt_pk_bf16_f32 v199, v120, v121
	v_cvt_pk_bf16_f32 v200, v114, v115
	v_cvt_pk_bf16_f32 v201, v116, v117
	v_add_u32_e32 v8, 0xc000, v138
	v_lshl_add_u64 v[144:145], v[8:9], 1, s[52:53]
	v_permlane16_swap_b32 v198, v200
	v_permlane16_swap_b32 v199, v201
	s_nop 1
	global_store_dwordx4 v[144:145], v[198:201], off
	v_cvt_pk_bf16_f32 v190, v110, v111
	v_cvt_pk_bf16_f32 v191, v112, v113
	v_cvt_pk_bf16_f32 v192, v106, v107
	v_cvt_pk_bf16_f32 v193, v108, v109
	v_add_u32_e32 v8, 0xc020, v138
	v_lshl_add_u64 v[202:203], v[8:9], 1, s[52:53]
	v_permlane16_swap_b32 v190, v192
	v_permlane16_swap_b32 v191, v193
	s_nop 1
	global_store_dwordx4 v[202:203], v[190:193], off
	v_cvt_pk_bf16_f32 v194, v102, v103
	v_cvt_pk_bf16_f32 v195, v104, v105
	v_cvt_pk_bf16_f32 v196, v98, v99
	v_cvt_pk_bf16_f32 v197, v100, v101
	v_add_u32_e32 v8, 0x18000, v138
	v_lshl_add_u64 v[204:205], v[8:9], 1, s[52:53]
	v_permlane16_swap_b32 v194, v196
	v_permlane16_swap_b32 v195, v197
	s_nop 1
	global_store_dwordx4 v[204:205], v[194:197], off
	v_cvt_pk_bf16_f32 v198, v94, v95
	v_cvt_pk_bf16_f32 v199, v96, v97
	v_cvt_pk_bf16_f32 v200, v90, v91
	v_cvt_pk_bf16_f32 v201, v92, v93
	v_add_u32_e32 v8, 0x18020, v138
	v_lshl_add_u64 v[144:145], v[8:9], 1, s[52:53]
	v_permlane16_swap_b32 v198, v200
	v_permlane16_swap_b32 v199, v201
	s_nop 1
	global_store_dwordx4 v[144:145], v[198:201], off
	v_cvt_pk_bf16_f32 v190, v86, v87
	v_cvt_pk_bf16_f32 v191, v88, v89
	v_cvt_pk_bf16_f32 v192, v82, v83
	v_cvt_pk_bf16_f32 v193, v84, v85
	v_add_u32_e32 v8, 0x24000, v138
	v_lshl_add_u64 v[202:203], v[8:9], 1, s[52:53]
	v_permlane16_swap_b32 v190, v192
	v_permlane16_swap_b32 v191, v193
	s_nop 1
	global_store_dwordx4 v[202:203], v[190:193], off
	v_cvt_pk_bf16_f32 v194, v78, v79
	v_cvt_pk_bf16_f32 v195, v80, v81
	v_cvt_pk_bf16_f32 v196, v74, v75
	v_cvt_pk_bf16_f32 v197, v76, v77
	v_add_u32_e32 v8, 0x24020, v138
	v_lshl_add_u64 v[204:205], v[8:9], 1, s[52:53]
	v_permlane16_swap_b32 v194, v196
	v_permlane16_swap_b32 v195, v197
	s_nop 1
	global_store_dwordx4 v[204:205], v[194:197], off
	v_cvt_pk_bf16_f32 v198, v70, v71
	v_cvt_pk_bf16_f32 v199, v72, v73
	v_cvt_pk_bf16_f32 v200, v66, v67
	v_cvt_pk_bf16_f32 v201, v68, v69
	v_add_u32_e32 v8, 0x30000, v138
	v_lshl_add_u64 v[144:145], v[8:9], 1, s[52:53]
	v_permlane16_swap_b32 v198, v200
	v_permlane16_swap_b32 v199, v201
	s_nop 1
	global_store_dwordx4 v[144:145], v[198:201], off
	v_cvt_pk_bf16_f32 v190, v62, v63
	v_cvt_pk_bf16_f32 v191, v64, v65
	v_cvt_pk_bf16_f32 v192, v58, v59
	v_cvt_pk_bf16_f32 v193, v60, v61
	v_add_u32_e32 v8, 0x30020, v138
	v_lshl_add_u64 v[202:203], v[8:9], 1, s[52:53]
	v_permlane16_swap_b32 v190, v192
	v_permlane16_swap_b32 v191, v193
	s_nop 1
	global_store_dwordx4 v[202:203], v[190:193], off
	v_cvt_pk_bf16_f32 v194, v54, v55
	v_cvt_pk_bf16_f32 v195, v56, v57
	v_cvt_pk_bf16_f32 v196, v50, v51
	v_cvt_pk_bf16_f32 v197, v52, v53
	v_add_u32_e32 v8, 0x3c000, v138
	v_lshl_add_u64 v[204:205], v[8:9], 1, s[52:53]
	v_permlane16_swap_b32 v194, v196
	v_permlane16_swap_b32 v195, v197
	s_nop 1
	global_store_dwordx4 v[204:205], v[194:197], off
	v_cvt_pk_bf16_f32 v198, v46, v47
	v_cvt_pk_bf16_f32 v199, v48, v49
	v_cvt_pk_bf16_f32 v200, v42, v43
	v_cvt_pk_bf16_f32 v201, v44, v45
	v_add_u32_e32 v8, 0x3c020, v138
	v_lshl_add_u64 v[144:145], v[8:9], 1, s[52:53]
	v_permlane16_swap_b32 v198, v200
	v_permlane16_swap_b32 v199, v201
	s_nop 1
	global_store_dwordx4 v[144:145], v[198:201], off
	v_cvt_pk_bf16_f32 v190, v38, v39
	v_cvt_pk_bf16_f32 v191, v40, v41
	v_cvt_pk_bf16_f32 v192, v34, v35
	v_cvt_pk_bf16_f32 v193, v36, v37
	v_add_u32_e32 v8, 0x48000, v138
	v_lshl_add_u64 v[202:203], v[8:9], 1, s[52:53]
	v_permlane16_swap_b32 v190, v192
	v_permlane16_swap_b32 v191, v193
	s_nop 1
	global_store_dwordx4 v[202:203], v[190:193], off
	v_cvt_pk_bf16_f32 v194, v30, v31
	v_cvt_pk_bf16_f32 v195, v32, v33
	v_cvt_pk_bf16_f32 v196, v26, v27
	v_cvt_pk_bf16_f32 v197, v28, v29
	v_add_u32_e32 v8, 0x48020, v138
	v_lshl_add_u64 v[204:205], v[8:9], 1, s[52:53]
	v_permlane16_swap_b32 v194, v196
	v_permlane16_swap_b32 v195, v197
	s_nop 1
	global_store_dwordx4 v[204:205], v[194:197], off
	v_cvt_pk_bf16_f32 v198, v22, v23
	v_cvt_pk_bf16_f32 v199, v24, v25
	v_cvt_pk_bf16_f32 v200, v18, v19
	v_cvt_pk_bf16_f32 v201, v20, v21
	v_add_u32_e32 v8, 0x54000, v138
	v_lshl_add_u64 v[144:145], v[8:9], 1, s[52:53]
	v_permlane16_swap_b32 v198, v200
	v_permlane16_swap_b32 v199, v201
	s_nop 1
	global_store_dwordx4 v[144:145], v[198:201], off
	v_cvt_pk_bf16_f32 v190, v14, v15
	v_cvt_pk_bf16_f32 v191, v16, v17
	v_cvt_pk_bf16_f32 v192, v10, v11
	v_cvt_pk_bf16_f32 v193, v12, v13
	v_add_u32_e32 v8, 0x54020, v138
	v_lshl_add_u64 v[202:203], v[8:9], 1, s[52:53]
	v_permlane16_swap_b32 v190, v192
	v_permlane16_swap_b32 v191, v193
	s_nop 1
	global_store_dwordx4 v[202:203], v[190:193], off
	s_setprio 0
	s_branch .LBB0_606

;     ...
;           for (int mi = 0; mi < MI; mi++)
; #pragma unroll
;             for (int ni = 0; ni < 4; ni++)
;               acc[mi][ni] = __builtin_amdgcn_mfma_f32_16x16x32_bf16(bfr[ni], af[mi], acc[mi][ni], 0, 0, 0);
;     ...
;             } else if constexpr (EPI == EPI_HYB) {
;               if (col >= 1024 && col < 1536) {
;                 const unsigned bb = row / (unsigned)LP;
;                 const unsigned vb_ = ((bb * 8u + ((col - 1024) >> 6)) * 64u + (col & 63)) * (unsigned)LP + (row - bb * (unsigned)LP);
;                 e.b1[vb_] = f2bf(a[0]); e.b1[vb_ + LP] = f2bf(a[1]); e.b1[vb_ + 2 * LP] = f2bf(a[2]); e.b1[vb_ + 3 * LP] = f2bf(a[3]);
;               } else if (col < ZLD) {
;                 uint2 o; o.x = pack2(a[0], a[1]); o.y = pack2(a[2], a[3]);
;                 *(uint2*)(e.b0 + (row * (unsigned)ZLD + col)) = o;
;               } else if (col < ZLD + 16) {
;                 *(float4*)(e.f0 + (row * 16u + (col - ZLD))) = make_float4(a[0], a[1], a[2], a[3]);
;               }
.Lhy_last:
	v_mfma_f32_16x16x32_bf16 v[134:137], v[198:201], v[138:141], v[134:137]
	v_mfma_f32_16x16x32_bf16 v[130:133], v[202:205], v[138:141], v[130:133]
	v_mfma_f32_16x16x32_bf16 v[126:129], v[226:229], v[138:141], v[126:129]
	v_mfma_f32_16x16x32_bf16 v[122:125], v[230:233], v[138:141], v[122:125]
	v_mfma_f32_16x16x32_bf16 v[118:121], v[198:201], v[170:173], v[118:121]
	v_mfma_f32_16x16x32_bf16 v[114:117], v[202:205], v[170:173], v[114:117]
	v_mfma_f32_16x16x32_bf16 v[110:113], v[226:229], v[170:173], v[110:113]
	v_mfma_f32_16x16x32_bf16 v[106:109], v[230:233], v[170:173], v[106:109]
	v_mfma_f32_16x16x32_bf16 v[102:105], v[198:201], v[174:177], v[102:105]
	v_mfma_f32_16x16x32_bf16 v[98:101], v[202:205], v[174:177], v[98:101]
	v_mfma_f32_16x16x32_bf16 v[94:97], v[226:229], v[174:177], v[94:97]
	v_mfma_f32_16x16x32_bf16 v[90:93], v[230:233], v[174:177], v[90:93]
	v_mfma_f32_16x16x32_bf16 v[86:89], v[198:201], v[178:181], v[86:89]
	v_mfma_f32_16x16x32_bf16 v[82:85], v[202:205], v[178:181], v[82:85]
	v_mfma_f32_16x16x32_bf16 v[78:81], v[226:229], v[178:181], v[78:81]
	v_mfma_f32_16x16x32_bf16 v[74:77], v[230:233], v[178:181], v[74:77]
	v_mfma_f32_16x16x32_bf16 v[70:73], v[198:201], v[182:185], v[70:73]
	v_mfma_f32_16x16x32_bf16 v[66:69], v[202:205], v[182:185], v[66:69]
	v_mfma_f32_16x16x32_bf16 v[62:65], v[226:229], v[182:185], v[62:65]
	v_mfma_f32_16x16x32_bf16 v[58:61], v[230:233], v[182:185], v[58:61]
	v_mfma_f32_16x16x32_bf16 v[54:57], v[198:201], v[186:189], v[54:57]
	v_mfma_f32_16x16x32_bf16 v[50:53], v[202:205], v[186:189], v[50:53]
	v_mfma_f32_16x16x32_bf16 v[46:49], v[226:229], v[186:189], v[46:49]
	v_mfma_f32_16x16x32_bf16 v[42:45], v[230:233], v[186:189], v[42:45]
	v_mfma_f32_16x16x32_bf16 v[38:41], v[198:201], v[190:193], v[38:41]
	v_mfma_f32_16x16x32_bf16 v[34:37], v[202:205], v[190:193], v[34:37]
	v_mfma_f32_16x16x32_bf16 v[30:33], v[226:229], v[190:193], v[30:33]
	v_mfma_f32_16x16x32_bf16 v[26:29], v[230:233], v[190:193], v[26:29]
	v_mfma_f32_16x16x32_bf16 v[22:25], v[198:201], v[194:197], v[22:25]
	v_mfma_f32_16x16x32_bf16 v[18:21], v[202:205], v[194:197], v[18:21]
	v_mfma_f32_16x16x32_bf16 v[14:17], v[226:229], v[194:197], v[14:17]
	v_mfma_f32_16x16x32_bf16 v[10:13], v[230:233], v[194:197], v[10:13]
	s_cmpk_gt_u32 s9, 0xdff
	s_cbranch_scc1 .Lhy_slow
	s_and_b32 s4, s6, 0x1fffffc
	s_cmp_eq_u32 s4, 8
	s_cbranch_scc1 .Lhy_slow
;     ...
;       const unsigned rb2 = (unsigned)(m0 + wm * (BM / 2) + fr);
;       const unsigned cb2 = (unsigned)(n0 + wn * 64 + fq * 4);
; #pragma unroll
;       for (int mi = 0; mi < MI; mi++) {
;         const unsigned row = rb2 + mi * 16;
;     ...
;             } else if constexpr (EPI == EPI_HYB) {
;               if (col >= 1024 && col < 1536) {
;                 const unsigned bb = row / (unsigned)LP;
;                 const unsigned vb_ = ((bb * 8u + ((col - 1024) >> 6)) * 64u + (col & 63)) * (unsigned)LP + (row - bb * (unsigned)LP);
;                 e.b1[vb_] = f2bf(a[0]); e.b1[vb_ + LP] = f2bf(a[1]); e.b1[vb_ + 2 * LP] = f2bf(a[2]); e.b1[vb_ + 3 * LP] = f2bf(a[3]);
;               } else if (col < ZLD) {
;                 uint2 o; o.x = pack2(a[0], a[1]); o.y = pack2(a[2], a[3]);
;                 *(uint2*)(e.b0 + (row * (unsigned)ZLD + col)) = o;
	s_setprio 2
	v_add_u32_e32 v234, s7, v153
	v_or_b32_e32 v234, v234, v151
	s_movk_i32 s4, 0xe00
	v_mul_lo_u32 v235, v234, s4
	v_or_b32_e32 v236, s9, v155
	v_add_u32_e32 v235, v235, v236
	v_bfe_u32 v236, v2, 4, 1
	v_mul_u32_u24_e32 v236, 12, v236
	s_nop 0
	v_add_u32_e32 v235, v235, v236
	v_cvt_pk_bf16_f32 v170, v134, v135
	v_cvt_pk_bf16_f32 v171, v136, v137
	v_cvt_pk_bf16_f32 v172, v130, v131
	v_cvt_pk_bf16_f32 v173, v132, v133
	v_mov_b32_e32 v8, v235
	v_lshl_add_u64 v[186:187], v[8:9], 1, s[52:53]
	v_permlane16_swap_b32 v170, v172
	v_permlane16_swap_b32 v171, v173
	s_nop 1
	global_store_dwordx4 v[186:187], v[170:173], off
	v_cvt_pk_bf16_f32 v174, v126, v127
	v_cvt_pk_bf16_f32 v175, v128, v129
	v_cvt_pk_bf16_f32 v176, v122, v123
	v_cvt_pk_bf16_f32 v177, v124, v125
	v_add_u32_e32 v8, 0x20, v235
	v_lshl_add_u64 v[188:189], v[8:9], 1, s[52:53]
	v_permlane16_swap_b32 v174, v176
	v_permlane16_swap_b32 v175, v177
	s_nop 1
	global_store_dwordx4 v[188:189], v[174:177], off
	v_cvt_pk_bf16_f32 v178, v118, v119
	v_cvt_pk_bf16_f32 v179, v120, v121
	v_cvt_pk_bf16_f32 v180, v114, v115
	v_cvt_pk_bf16_f32 v181, v116, v117
	v_add_u32_e32 v8, 0xe000, v235
	v_lshl_add_u64 v[190:191], v[8:9], 1, s[52:53]
	v_permlane16_swap_b32 v178, v180
	v_permlane16_swap_b32 v179, v181
	s_nop 1
	global_store_dwordx4 v[190:191], v[178:181], off
	v_cvt_pk_bf16_f32 v182, v110, v111
	v_cvt_pk_bf16_f32 v183, v112, v113
	v_cvt_pk_bf16_f32 v184, v106, v107
	v_cvt_pk_bf16_f32 v185, v108, v109
	v_add_u32_e32 v8, 0xe020, v235
	v_lshl_add_u64 v[192:193], v[8:9], 1, s[52:53]
	v_permlane16_swap_b32 v182, v184
	v_permlane16_swap_b32 v183, v185
	s_nop 1
	global_store_dwordx4 v[192:193], v[182:185], off
	v_cvt_pk_bf16_f32 v170, v102, v103
	v_cvt_pk_bf16_f32 v171, v104, v105
	v_cvt_pk_bf16_f32 v172, v98, v99
	v_cvt_pk_bf16_f32 v173, v100, v101
	v_add_u32_e32 v8, 0x1c000, v235
	v_lshl_add_u64 v[186:187], v[8:9], 1, s[52:53]
	v_permlane16_swap_b32 v170, v172
	v_permlane16_swap_b32 v171, v173
	s_nop 1
	global_store_dwordx4 v[186:187], v[170:173], off
	v_cvt_pk_bf16_f32 v174, v94, v95
	v_cvt_pk_bf16_f32 v175, v96, v97
	v_cvt_pk_bf16_f32 v176, v90, v91
	v_cvt_pk_bf16_f32 v177, v92, v93
	v_add_u32_e32 v8, 0x1c020, v235
	v_lshl_add_u64 v[188:189], v[8:9], 1, s[52:53]
	v_permlane16_swap_b32 v174, v176
	v_permlane16_swap_b32 v175, v177
	s_nop 1
	global_store_dwordx4 v[188:189], v[174:177], off
	v_cvt_pk_bf16_f32 v178, v86, v87
	v_cvt_pk_bf16_f32 v179, v88, v89
	v_cvt_pk_bf16_f32 v180, v82, v83
	v_cvt_pk_bf16_f32 v181, v84, v85
	v_add_u32_e32 v8, 0x2a000, v235
	v_lshl_add_u64 v[190:191], v[8:9], 1, s[52:53]
	v_permlane16_swap_b32 v178, v180
	v_permlane16_swap_b32 v179, v181
	s_nop 1
	global_store_dwordx4 v[190:191], v[178:181], off
	v_cvt_pk_bf16_f32 v182, v78, v79
	v_cvt_pk_bf16_f32 v183, v80, v81
	v_cvt_pk_bf16_f32 v184, v74, v75
	v_cvt_pk_bf16_f32 v185, v76, v77
	v_add_u32_e32 v8, 0x2a020, v235
	v_lshl_add_u64 v[192:193], v[8:9], 1, s[52:53]
	v_permlane16_swap_b32 v182, v184
	v_permlane16_swap_b32 v183, v185
	s_nop 1
	global_store_dwordx4 v[192:193], v[182:185], off
	v_cvt_pk_bf16_f32 v170, v70, v71
	v_cvt_pk_bf16_f32 v171, v72, v73
	v_cvt_pk_bf16_f32 v172, v66, v67
	v_cvt_pk_bf16_f32 v173, v68, v69
	v_add_u32_e32 v8, 0x38000, v235
	v_lshl_add_u64 v[186:187], v[8:9], 1, s[52:53]
	v_permlane16_swap_b32 v170, v172
	v_permlane16_swap_b32 v171, v173
	s_nop 1
	global_store_dwordx4 v[186:187], v[170:173], off
	v_cvt_pk_bf16_f32 v174, v62, v63
	v_cvt_pk_bf16_f32 v175, v64, v65
	v_cvt_pk_bf16_f32 v176, v58, v59
	v_cvt_pk_bf16_f32 v177, v60, v61
	v_add_u32_e32 v8, 0x38020, v235
	v_lshl_add_u64 v[188:189], v[8:9], 1, s[52:53]
	v_permlane16_swap_b32 v174, v176
	v_permlane16_swap_b32 v175, v177
	s_nop 1
	global_store_dwordx4 v[188:189], v[174:177], off
	v_cvt_pk_bf16_f32 v178, v54, v55
	v_cvt_pk_bf16_f32 v179, v56, v57
	v_cvt_pk_bf16_f32 v180, v50, v51
	v_cvt_pk_bf16_f32 v181, v52, v53
	v_add_u32_e32 v8, 0x46000, v235
	v_lshl_add_u64 v[190:191], v[8:9], 1, s[52:53]
	v_permlane16_swap_b32 v178, v180
	v_permlane16_swap_b32 v179, v181
	s_nop 1
	global_store_dwordx4 v[190:191], v[178:181], off
	v_cvt_pk_bf16_f32 v182, v46, v47
	v_cvt_pk_bf16_f32 v183, v48, v49
	v_cvt_pk_bf16_f32 v184, v42, v43
	v_cvt_pk_bf16_f32 v185, v44, v45
	v_add_u32_e32 v8, 0x46020, v235
	v_lshl_add_u64 v[192:193], v[8:9], 1, s[52:53]
	v_permlane16_swap_b32 v182, v184
	v_permlane16_swap_b32 v183, v185
	s_nop 1
	global_store_dwordx4 v[192:193], v[182:185], off
	v_cvt_pk_bf16_f32 v170, v38, v39
	v_cvt_pk_bf16_f32 v171, v40, v41
	v_cvt_pk_bf16_f32 v172, v34, v35
	v_cvt_pk_bf16_f32 v173, v36, v37
	v_add_u32_e32 v8, 0x54000, v235
	v_lshl_add_u64 v[186:187], v[8:9], 1, s[52:53]
	v_permlane16_swap_b32 v170, v172
	v_permlane16_swap_b32 v171, v173
	s_nop 1
	global_store_dwordx4 v[186:187], v[170:173], off
	v_cvt_pk_bf16_f32 v174, v30, v31
	v_cvt_pk_bf16_f32 v175, v32, v33
	v_cvt_pk_bf16_f32 v176, v26, v27
	v_cvt_pk_bf16_f32 v177, v28, v29
	v_add_u32_e32 v8, 0x54020, v235
	v_lshl_add_u64 v[188:189], v[8:9], 1, s[52:53]
	v_permlane16_swap_b32 v174, v176
	v_permlane16_swap_b32 v175, v177
	s_nop 1
	global_store_dwordx4 v[188:189], v[174:177], off
	v_cvt_pk_bf16_f32 v178, v22, v23
	v_cvt_pk_bf16_f32 v179, v24, v25
	v_cvt_pk_bf16_f32 v180, v18, v19
	v_cvt_pk_bf16_f32 v181, v20, v21
	v_add_u32_e32 v8, 0x62000, v235
	v_lshl_add_u64 v[190:191], v[8:9], 1, s[52:53]
	v_permlane16_swap_b32 v178, v180
	v_permlane16_swap_b32 v179, v181
	s_nop 1
	global_store_dwordx4 v[190:191], v[178:181], off
	v_cvt_pk_bf16_f32 v182, v14, v15
	v_cvt_pk_bf16_f32 v183, v16, v17
	v_cvt_pk_bf16_f32 v184, v10, v11
	v_cvt_pk_bf16_f32 v185, v12, v13
	v_add_u32_e32 v8, 0x62020, v235
	v_lshl_add_u64 v[192:193], v[8:9], 1, s[52:53]
	v_permlane16_swap_b32 v182, v184
	v_permlane16_swap_b32 v183, v185
	s_nop 1
	global_store_dwordx4 v[192:193], v[182:185], off
	s_setprio 0
	s_branch .LBB0_2183

;     ...
;           for (int ni = 0; ni < 4; ni++) {
;             const unsigned col = cb2 + ni * 16;
;             const f32x4 a = acc[mi][ni];
;             if constexpr (EPI == EPI_RESID) {
;               if (pr >= PADR) {
;                 float4* hp = (float4*)(e.f0 + (row * (unsigned)D + col));
;                 float4 hv = *hp;
;                 hv.x += e.alpha * a[0]; hv.y += e.alpha * a[1]; hv.z += e.alpha * a[2]; hv.w += e.alpha * a[3];
;                 *hp = hv;
;               }
.LBB0_2575:
	s_setprio 2
	v_add_u32_e32 v202, s17, v152
	v_or_b32_e32 v203, s18, v153
	v_readlane_b32 s22, v247, 3
	v_readlane_b32 s23, v247, 4
	v_readlane_b32 s20, v244, 15
	v_readlane_b32 s21, v244, 16
	s_mov_b32 s2, 0xfc0fc0fd
	s_movk_i32 s19, 0x6f
	v_mov_b32_e32 v204, v202
	v_mul_hi_u32 v226, v204, s2
	v_lshl_add_u32 v8, v204, 10, v203
	v_lshrrev_b32_e32 v226, 13, v226
	v_lshl_add_u64 v[198:199], v[8:9], 2, s[22:23]
	v_mul_u32_u24_e32 v226, 0x2080, v226
	v_sub_u32_e32 v226, v204, v226
	v_cmp_lt_u32_e64 s[24:25], s19, v226
	v_add_u32_e32 v205, 16, v202
	v_mul_hi_u32 v227, v205, s2
	v_lshl_add_u32 v8, v205, 10, v203
	v_lshrrev_b32_e32 v227, 13, v227
	v_lshl_add_u64 v[200:201], v[8:9], 2, s[22:23]
	v_mul_u32_u24_e32 v227, 0x2080, v227
	v_sub_u32_e32 v227, v205, v227
	v_cmp_lt_u32_e64 s[26:27], s19, v227
	s_mov_b64 exec, s[24:25]
	global_load_dwordx4 v[166:169], v[198:199], off
	global_load_dwordx4 v[170:173], v[198:199], off offset:64
	global_load_dwordx4 v[174:177], v[198:199], off offset:128
	global_load_dwordx4 v[178:181], v[198:199], off offset:192
	s_mov_b64 exec, s[26:27]
	global_load_dwordx4 v[182:185], v[200:201], off
	global_load_dwordx4 v[186:189], v[200:201], off offset:64
	global_load_dwordx4 v[190:193], v[200:201], off offset:128
	global_load_dwordx4 v[194:197], v[200:201], off offset:192
	s_mov_b64 exec, -1
	s_waitcnt vmcnt(0)
	v_pk_fma_f32 v[134:135], s[20:21], v[134:135], v[166:167]
	v_pk_fma_f32 v[136:137], s[20:21], v[136:137], v[168:169]
	v_pk_fma_f32 v[130:131], s[20:21], v[130:131], v[170:171]
	v_pk_fma_f32 v[132:133], s[20:21], v[132:133], v[172:173]
	v_pk_fma_f32 v[126:127], s[20:21], v[126:127], v[174:175]
	v_pk_fma_f32 v[128:129], s[20:21], v[128:129], v[176:177]
	v_pk_fma_f32 v[122:123], s[20:21], v[122:123], v[178:179]
	v_pk_fma_f32 v[124:125], s[20:21], v[124:125], v[180:181]
	v_pk_fma_f32 v[118:119], s[20:21], v[118:119], v[182:183]
	v_pk_fma_f32 v[120:121], s[20:21], v[120:121], v[184:185]
	v_pk_fma_f32 v[114:115], s[20:21], v[114:115], v[186:187]
	v_pk_fma_f32 v[116:117], s[20:21], v[116:117], v[188:189]
	v_pk_fma_f32 v[110:111], s[20:21], v[110:111], v[190:191]
	v_pk_fma_f32 v[112:113], s[20:21], v[112:113], v[192:193]
	v_pk_fma_f32 v[106:107], s[20:21], v[106:107], v[194:195]
	v_pk_fma_f32 v[108:109], s[20:21], v[108:109], v[196:197]
	s_mov_b64 exec, s[24:25]
	global_store_dwordx4 v[198:199], v[134:137], off
	global_store_dwordx4 v[198:199], v[130:133], off offset:64
	global_store_dwordx4 v[198:199], v[126:129], off offset:128
	global_store_dwordx4 v[198:199], v[122:125], off offset:192
	s_mov_b64 exec, s[26:27]
	global_store_dwordx4 v[200:201], v[118:121], off
	global_store_dwordx4 v[200:201], v[114:117], off offset:64
	global_store_dwordx4 v[200:201], v[110:113], off offset:128
	global_store_dwordx4 v[200:201], v[106:109], off offset:192
	s_mov_b64 exec, -1
	v_add_u32_e32 v204, 32, v202
	v_mul_hi_u32 v226, v204, s2
	v_lshl_add_u32 v8, v204, 10, v203
	v_lshrrev_b32_e32 v226, 13, v226
	v_lshl_add_u64 v[198:199], v[8:9], 2, s[22:23]
	v_mul_u32_u24_e32 v226, 0x2080, v226
	v_sub_u32_e32 v226, v204, v226
	v_cmp_lt_u32_e64 s[24:25], s19, v226
	v_add_u32_e32 v205, 48, v202
	v_mul_hi_u32 v227, v205, s2
	v_lshl_add_u32 v8, v205, 10, v203
	v_lshrrev_b32_e32 v227, 13, v227
	v_lshl_add_u64 v[200:201], v[8:9], 2, s[22:23]
	v_mul_u32_u24_e32 v227, 0x2080, v227
	v_sub_u32_e32 v227, v205, v227
	v_cmp_lt_u32_e64 s[26:27], s19, v227
	s_mov_b64 exec, s[24:25]
	global_load_dwordx4 v[166:169], v[198:199], off
	global_load_dwordx4 v[170:173], v[198:199], off offset:64
	global_load_dwordx4 v[174:177], v[198:199], off offset:128
	global_load_dwordx4 v[178:181], v[198:199], off offset:192
	s_mov_b64 exec, s[26:27]
	global_load_dwordx4 v[182:185], v[200:201], off
	global_load_dwordx4 v[186:189], v[200:201], off offset:64
	global_load_dwordx4 v[190:193], v[200:201], off offset:128
	global_load_dwordx4 v[194:197], v[200:201], off offset:192
	s_mov_b64 exec, -1
	s_waitcnt vmcnt(0)
;     ...
;           for (int ni = 0; ni < 4; ni++) {
;             const unsigned col = cb2 + ni * 16;
;             const f32x4 a = acc[mi][ni];
;             if constexpr (EPI == EPI_RESID) {
;               if (pr >= PADR) {
;                 float4* hp = (float4*)(e.f0 + (row * (unsigned)D + col));
;                 float4 hv = *hp;
;                 hv.x += e.alpha * a[0]; hv.y += e.alpha * a[1]; hv.z += e.alpha * a[2]; hv.w += e.alpha * a[3];
;                 *hp = hv;
;               }
	v_pk_fma_f32 v[102:103], s[20:21], v[102:103], v[166:167]
	v_pk_fma_f32 v[104:105], s[20:21], v[104:105], v[168:169]
	v_pk_fma_f32 v[98:99], s[20:21], v[98:99], v[170:171]
	v_pk_fma_f32 v[100:101], s[20:21], v[100:101], v[172:173]
	v_pk_fma_f32 v[94:95], s[20:21], v[94:95], v[174:175]
	v_pk_fma_f32 v[96:97], s[20:21], v[96:97], v[176:177]
	v_pk_fma_f32 v[90:91], s[20:21], v[90:91], v[178:179]
	v_pk_fma_f32 v[92:93], s[20:21], v[92:93], v[180:181]
	v_pk_fma_f32 v[86:87], s[20:21], v[86:87], v[182:183]
	v_pk_fma_f32 v[88:89], s[20:21], v[88:89], v[184:185]
	v_pk_fma_f32 v[82:83], s[20:21], v[82:83], v[186:187]
	v_pk_fma_f32 v[84:85], s[20:21], v[84:85], v[188:189]
	v_pk_fma_f32 v[78:79], s[20:21], v[78:79], v[190:191]
	v_pk_fma_f32 v[80:81], s[20:21], v[80:81], v[192:193]
	v_pk_fma_f32 v[74:75], s[20:21], v[74:75], v[194:195]
	v_pk_fma_f32 v[76:77], s[20:21], v[76:77], v[196:197]
	s_mov_b64 exec, s[24:25]
	global_store_dwordx4 v[198:199], v[102:105], off
	global_store_dwordx4 v[198:199], v[98:101], off offset:64
	global_store_dwordx4 v[198:199], v[94:97], off offset:128
	global_store_dwordx4 v[198:199], v[90:93], off offset:192
	s_mov_b64 exec, s[26:27]
	global_store_dwordx4 v[200:201], v[86:89], off
	global_store_dwordx4 v[200:201], v[82:85], off offset:64
	global_store_dwordx4 v[200:201], v[78:81], off offset:128
	global_store_dwordx4 v[200:201], v[74:77], off offset:192
	s_mov_b64 exec, -1
	v_add_u32_e32 v204, 64, v202
	v_mul_hi_u32 v226, v204, s2
	v_lshl_add_u32 v8, v204, 10, v203
	v_lshrrev_b32_e32 v226, 13, v226
	v_lshl_add_u64 v[198:199], v[8:9], 2, s[22:23]
	v_mul_u32_u24_e32 v226, 0x2080, v226
	v_sub_u32_e32 v226, v204, v226
	v_cmp_lt_u32_e64 s[24:25], s19, v226
	v_add_u32_e32 v205, 80, v202
	v_mul_hi_u32 v227, v205, s2
	v_lshl_add_u32 v8, v205, 10, v203
	v_lshrrev_b32_e32 v227, 13, v227
	v_lshl_add_u64 v[200:201], v[8:9], 2, s[22:23]
	v_mul_u32_u24_e32 v227, 0x2080, v227
	v_sub_u32_e32 v227, v205, v227
	v_cmp_lt_u32_e64 s[26:27], s19, v227
	s_mov_b64 exec, s[24:25]
	global_load_dwordx4 v[166:169], v[198:199], off
	global_load_dwordx4 v[170:173], v[198:199], off offset:64
	global_load_dwordx4 v[174:177], v[198:199], off offset:128
	global_load_dwordx4 v[178:181], v[198:199], off offset:192
	s_mov_b64 exec, s[26:27]
	global_load_dwordx4 v[182:185], v[200:201], off
	global_load_dwordx4 v[186:189], v[200:201], off offset:64
	global_load_dwordx4 v[190:193], v[200:201], off offset:128
	global_load_dwordx4 v[194:197], v[200:201], off offset:192
	s_mov_b64 exec, -1
	s_waitcnt vmcnt(0)
	v_pk_fma_f32 v[70:71], s[20:21], v[70:71], v[166:167]
	v_pk_fma_f32 v[72:73], s[20:21], v[72:73], v[168:169]
	v_pk_fma_f32 v[66:67], s[20:21], v[66:67], v[170:171]
	v_pk_fma_f32 v[68:69], s[20:21], v[68:69], v[172:173]
	v_pk_fma_f32 v[62:63], s[20:21], v[62:63], v[174:175]
	v_pk_fma_f32 v[64:65], s[20:21], v[64:65], v[176:177]
	v_pk_fma_f32 v[58:59], s[20:21], v[58:59], v[178:179]
	v_pk_fma_f32 v[60:61], s[20:21], v[60:61], v[180:181]
	v_pk_fma_f32 v[54:55], s[20:21], v[54:55], v[182:183]
	v_pk_fma_f32 v[56:57], s[20:21], v[56:57], v[184:185]
	v_pk_fma_f32 v[50:51], s[20:21], v[50:51], v[186:187]
	v_pk_fma_f32 v[52:53], s[20:21], v[52:53], v[188:189]
	v_pk_fma_f32 v[46:47], s[20:21], v[46:47], v[190:191]
	v_pk_fma_f32 v[48:49], s[20:21], v[48:49], v[192:193]
	v_pk_fma_f32 v[42:43], s[20:21], v[42:43], v[194:195]
	v_pk_fma_f32 v[44:45], s[20:21], v[44:45], v[196:197]
	s_mov_b64 exec, s[24:25]
	global_store_dwordx4 v[198:199], v[70:73], off
	global_store_dwordx4 v[198:199], v[66:69], off offset:64
	global_store_dwordx4 v[198:199], v[62:65], off offset:128
	global_store_dwordx4 v[198:199], v[58:61], off offset:192
	s_mov_b64 exec, s[26:27]
	global_store_dwordx4 v[200:201], v[54:57], off
	global_store_dwordx4 v[200:201], v[50:53], off offset:64
	global_store_dwordx4 v[200:201], v[46:49], off offset:128
	global_store_dwordx4 v[200:201], v[42:45], off offset:192
	s_mov_b64 exec, -1
	v_add_u32_e32 v204, 96, v202
	v_mul_hi_u32 v226, v204, s2
	v_lshl_add_u32 v8, v204, 10, v203
	v_lshrrev_b32_e32 v226, 13, v226
	v_lshl_add_u64 v[198:199], v[8:9], 2, s[22:23]
	v_mul_u32_u24_e32 v226, 0x2080, v226
	v_sub_u32_e32 v226, v204, v226
	v_cmp_lt_u32_e64 s[24:25], s19, v226
	v_add_u32_e32 v205, 112, v202
	v_mul_hi_u32 v227, v205, s2
	v_lshl_add_u32 v8, v205, 10, v203
	v_lshrrev_b32_e32 v227, 13, v227
	v_lshl_add_u64 v[200:201], v[8:9], 2, s[22:23]
	v_mul_u32_u24_e32 v227, 0x2080, v227
	v_sub_u32_e32 v227, v205, v227
	v_cmp_lt_u32_e64 s[26:27], s19, v227
	s_mov_b64 exec, s[24:25]
	global_load_dwordx4 v[166:169], v[198:199], off
	global_load_dwordx4 v[170:173], v[198:199], off offset:64
	global_load_dwordx4 v[174:177], v[198:199], off offset:128
	global_load_dwordx4 v[178:181], v[198:199], off offset:192
	s_mov_b64 exec, s[26:27]
	global_load_dwordx4 v[182:185], v[200:201], off
	global_load_dwordx4 v[186:189], v[200:201], off offset:64
	global_load_dwordx4 v[190:193], v[200:201], off offset:128
	global_load_dwordx4 v[194:197], v[200:201], off offset:192
	s_mov_b64 exec, -1
	s_waitcnt vmcnt(0)
	v_pk_fma_f32 v[38:39], s[20:21], v[38:39], v[166:167]
	v_pk_fma_f32 v[40:41], s[20:21], v[40:41], v[168:169]
	v_pk_fma_f32 v[34:35], s[20:21], v[34:35], v[170:171]
	v_pk_fma_f32 v[36:37], s[20:21], v[36:37], v[172:173]
	v_pk_fma_f32 v[30:31], s[20:21], v[30:31], v[174:175]
	v_pk_fma_f32 v[32:33], s[20:21], v[32:33], v[176:177]
	v_pk_fma_f32 v[26:27], s[20:21], v[26:27], v[178:179]
	v_pk_fma_f32 v[28:29], s[20:21], v[28:29], v[180:181]
	v_pk_fma_f32 v[22:23], s[20:21], v[22:23], v[182:183]
	v_pk_fma_f32 v[24:25], s[20:21], v[24:25], v[184:185]
	v_pk_fma_f32 v[18:19], s[20:21], v[18:19], v[186:187]
	v_pk_fma_f32 v[20:21], s[20:21], v[20:21], v[188:189]
	v_pk_fma_f32 v[14:15], s[20:21], v[14:15], v[190:191]
	v_pk_fma_f32 v[16:17], s[20:21], v[16:17], v[192:193]
	v_pk_fma_f32 v[10:11], s[20:21], v[10:11], v[194:195]
	v_pk_fma_f32 v[12:13], s[20:21], v[12:13], v[196:197]
	s_mov_b64 exec, s[24:25]
	global_store_dwordx4 v[198:199], v[38:41], off
	global_store_dwordx4 v[198:199], v[34:37], off offset:64
	global_store_dwordx4 v[198:199], v[30:33], off offset:128
	global_store_dwordx4 v[198:199], v[26:29], off offset:192
	s_mov_b64 exec, s[26:27]
	global_store_dwordx4 v[200:201], v[22:25], off
	global_store_dwordx4 v[200:201], v[18:21], off offset:64
	global_store_dwordx4 v[200:201], v[14:17], off offset:128
	global_store_dwordx4 v[200:201], v[10:13], off offset:192
	s_mov_b64 exec, -1
	s_setprio 0
	s_branch .Lre_latch
